# v2 + accumulator zeroing with v_mov_b64 + grid-size guard keeping the generic scan for grids other than 256 workgroups
# speedup vs baseline: 1.0215x; 1.0012x over previous
; template <class Epi, class Sched, bool ALIGN_EPI = false, bool SP2 = false>
; __device__ __forceinline__ void gemm_phase(PG8_LAS unsigned char* lds, const Gemm g, const Sched& S, const Epi& E) {
;     ...
;         const bool has_next = S.next(ui + 1, nxt);
;         const char* nA = has_next ? (const char*)g.A + (size_t)nxt.pm * tA + (size_t)nxt.pn * pnA : cA; const char* nB = has_next ? (const char*)g.Bt + (size_t)nxt.pn * tB : cB;
;     ...
; #pragma unroll
;         for (int a = 0; a < 2; ++a)
; #pragma unroll
;             for (int b = 0; b < 2; ++b)
; #pragma unroll
;                 for (int m = 0; m < 4; ++m)
; #pragma unroll
;                     for (int n = 0; n < 2; ++n) acc[a][b][m][n] = (f32x4){0.f, 0.f, 0.f, 0.f};
;         cur = nxt; cA = nA; cB = nB; ++ui;
.LBB0_189:
	s_ashr_i32 s55, s54, 31
	s_lshl_b64 s[56:57], s[54:55], 20
	s_add_u32 s56, s69, s56
	s_addc_u32 s57, s70, s57
	s_and_b64 s[58:59], s[8:9], exec
	s_cselect_b32 s11, s57, s63
	s_cselect_b32 s33, s56, s62
	s_ashr_i32 s53, s52, 31
	s_lshl_b64 s[58:59], s[52:53], 20
	s_add_u32 s58, s71, s58
	s_addc_u32 s59, s72, s59
	s_and_b64 s[66:67], s[8:9], exec
	s_cselect_b32 s53, s59, s65
	s_cselect_b32 s55, s58, s64
	s_add_u32 s62, s62, 0x80080
	s_addc_u32 s63, s63, 0
	s_add_u32 s61, s64, 0x100
	v_mov_b32_e32 v2, 0
	s_addc_u32 s96, s65, 0
	s_mov_b32 s97, -2
	v_mov_b32_e32 v3, v2
	v_mov_b64_e32 v[4:5], 0
	v_mov_b64_e32 v[6:7], 0
	v_mov_b64_e32 v[8:9], 0
	v_mov_b64_e32 v[10:11], 0
	v_mov_b64_e32 v[12:13], 0
	v_mov_b64_e32 v[14:15], 0
	v_mov_b64_e32 v[16:17], 0
	v_mov_b64_e32 v[18:19], 0
	v_mov_b64_e32 v[20:21], 0
	v_mov_b64_e32 v[22:23], 0
	v_mov_b64_e32 v[24:25], 0
	v_mov_b64_e32 v[26:27], 0
	v_mov_b64_e32 v[28:29], 0
	v_mov_b64_e32 v[30:31], 0
	v_mov_b64_e32 v[32:33], 0
	v_mov_b64_e32 v[34:35], 0
	v_mov_b64_e32 v[36:37], 0
	v_mov_b64_e32 v[38:39], 0
	v_mov_b64_e32 v[40:41], 0
	v_mov_b64_e32 v[42:43], 0
	v_mov_b64_e32 v[44:45], 0
	v_mov_b64_e32 v[46:47], 0
	v_mov_b64_e32 v[48:49], 0
	v_mov_b64_e32 v[50:51], 0
	v_mov_b64_e32 v[52:53], 0
	v_mov_b64_e32 v[54:55], 0
	v_mov_b64_e32 v[56:57], 0
	v_mov_b64_e32 v[58:59], 0
	v_mov_b64_e32 v[60:61], 0
	v_mov_b64_e32 v[62:63], 0
	v_mov_b64_e32 v[64:65], 0
	v_mov_b64_e32 v[66:67], 0
	v_mov_b64_e32 v[68:69], 0
	v_mov_b64_e32 v[70:71], 0
	v_mov_b64_e32 v[72:73], 0
	v_mov_b64_e32 v[74:75], 0
	v_mov_b64_e32 v[76:77], 0
	v_mov_b64_e32 v[78:79], 0
	v_mov_b64_e32 v[80:81], 0
	v_mov_b64_e32 v[82:83], 0
	v_mov_b64_e32 v[84:85], 0
	v_mov_b64_e32 v[86:87], 0
	v_mov_b64_e32 v[88:89], 0
	v_mov_b64_e32 v[90:91], 0
	v_mov_b64_e32 v[92:93], 0
	v_mov_b64_e32 v[94:95], 0
	v_mov_b64_e32 v[96:97], 0
	v_mov_b64_e32 v[98:99], 0
	v_mov_b64_e32 v[100:101], 0
	v_mov_b64_e32 v[102:103], 0
	v_mov_b64_e32 v[104:105], 0
	v_mov_b64_e32 v[106:107], 0
	v_mov_b64_e32 v[108:109], 0
	v_mov_b64_e32 v[110:111], 0
	v_mov_b64_e32 v[112:113], 0
	v_mov_b64_e32 v[114:115], 0
	v_mov_b64_e32 v[116:117], 0
	v_mov_b64_e32 v[118:119], 0
	v_mov_b64_e32 v[120:121], 0
	v_mov_b64_e32 v[122:123], 0
	v_mov_b64_e32 v[124:125], 0
	v_mov_b64_e32 v[126:127], 0
	v_mov_b64_e32 v[128:129], 0

; #define LAS __attribute__((address_space(3)))
; __device__ __forceinline__ float head_lg2(int h) { return log2f(1.0f - exp2f(-5.0f - (float)h)); }
; __device__ __forceinline__ void scan_phase(const bf16* q, const bf16* kdT, const bf16* vT, const bf16* Pp, bf16* o, LAS unsigned char* lds, int bid, int G, int wave, int lane, int tid) {
;     const int rnt = tid >> 8, rj = (tid >> 6) & 3, rhh = (tid >> 5) & 1, rv = tid & 31, rn0 = 32 * rnt + 8 * rj + 4 * rhh;
;     for (int unit = bid; unit < 256; unit += G) {
;         const int bh = (unit & 7) * 4 + (unit >> 6), vs = (unit >> 3) & 7, b = bh >> 3, h = bh & 7;
;         const float lg2 = head_lg2(h), cd = exp2f(64.0f * lg2);
;         float qd[4];
; #pragma unroll
;         for (int e = 0; e < 4; ++e) qd[e] = exp2f((float)(rn0 + e + 1) * lg2);
;         const char* kp = (const char*)kdT + ((size_t)bh * 64 * 16384 + wave * 2048) * 2;
;         const char* vp = (const char*)vT + ((size_t)bh * 64 * 16384 + vs * 2048) * 2;
;         const char* qp = (const char*)q + ((size_t)bh * 64 * 16384 + wave * 2048) * 2;
;         const char* pp = (const char*)Pp + ((size_t)bh * 64 * 4096 + wave * 512) * 2;
;         const unsigned voff = (unsigned)lane * 16u;
;         bf16* op = o + (size_t)(b * SEQ + rn0) * 2048 + h * 256 + 32 * vs + rv;
;         const int iks = wave & 3, int_ = wave >> 2;
;         const int rboff = ((rnt * 2 + (rj >> 1)) * 64 + rhh * 32 + rv) * 16 + (rj & 1) * 8;
.LBB0_431:
	s_or_b64 exec, exec, s[0:1]
	s_cmpk_lt_i32 s2, 0x100
	s_cselect_b64 s[10:11], -1, 0
	s_waitcnt vmcnt(31)
	v_mov_b32_e32 v2, v0
	s_waitcnt lgkmcnt(0)
	s_barrier
	s_mov_b64 s[12:13], s[30:31]
	v_readfirstlane_b32 s0, v2
	s_and_b64 vcc, exec, s[10:11]
	s_cbranch_vccz .LBB0_719
	s_load_dword s4, s[84:85], 0x0
	s_waitcnt lgkmcnt(0)
	s_cmp_eq_u32 s4, 0x100
	s_cbranch_scc0 .Lp2b_generic
	s_lshr_b32 s4, s0, 6
	s_and_b32 s6, s4, 3
	s_lshr_b32 s7, s4, 2
	s_movk_i32 s23, 0x7fff
	s_cmp_lt_u32 s4, 4
	s_cselect_b64 s[34:35], -1, 0
	v_and_b32_e32 v1, 63, v0
	v_lshlrev_b32_e32 v1, 4, v1
	s_and_b32 s52, s2, 7
	s_lshl_b32 s52, s52, 2
	s_lshr_b32 s53, s2, 6
	s_add_i32 s52, s52, s53
	s_bfe_u32 s53, s2, 0x30003
	s_lshr_b32 s54, s52, 3
	s_and_b32 s55, s52, 7
	s_lshl_b32 s56, s52, 21
	s_lshl_b32 s57, s4, 12
	s_add_u32 s58, s56, s57
	s_add_u32 s8, s30, s58
	s_addc_u32 s9, s31, 0
	s_add_u32 s8, s8, 0x5800000
	s_addc_u32 s9, s9, 0
	s_add_u32 s14, s30, s58
	s_addc_u32 s15, s31, 0
	s_add_u32 s14, s14, 0x11800000
	s_addc_u32 s15, s15, 0
	s_lshl_b32 s59, s53, 12
	s_add_u32 s59, s59, s56
	s_lshl_b32 s60, s6, 10
	s_add_u32 s59, s59, s60
	s_add_u32 s16, s30, s59
	s_addc_u32 s17, s31, 0
	s_add_u32 s16, s16, 0xd800000
	s_addc_u32 s17, s17, 0
	s_lshl_b32 s59, s52, 19
	s_lshl_b32 s60, s4, 10
	s_add_u32 s59, s59, s60
	s_add_u32 s18, s30, s59
	s_addc_u32 s19, s31, 0
	s_add_u32 s18, s18, 0x19800000
	s_addc_u32 s19, s19, 0
	s_lshl_b32 s59, s54, 24
	s_lshl_b32 s60, s55, 9
	s_add_u32 s59, s59, s60
	s_lshl_b32 s60, s53, 6
	s_add_u32 s59, s59, s60
	s_add_u32 s20, s30, s59
	s_addc_u32 s21, s31, 0
	s_add_u32 s20, s20, 0x9800000
	s_addc_u32 s21, s21, 0
	global_load_dwordx4 v[118:121], v1, s[14:15]
	global_load_dwordx4 v[122:125], v1, s[14:15] offset:1024
	global_load_dwordx4 v[126:129], v1, s[14:15] offset:2048
	global_load_dwordx4 v[130:133], v1, s[14:15] offset:3072
	global_load_dwordx4 v[58:61], v1, s[8:9]
	global_load_dwordx4 v[62:65], v1, s[8:9] offset:1024
	global_load_dwordx4 v[66:69], v1, s[8:9] offset:2048
	global_load_dwordx4 v[70:73], v1, s[8:9] offset:3072
	global_load_dwordx4 v[74:77], v1, s[18:19]
	s_add_u32 s8, s8, 0x8000
	s_addc_u32 s9, s9, 0
	s_add_u32 s18, s18, 0x2000
	s_addc_u32 s19, s19, 0
	global_load_dwordx4 v[78:81], v1, s[8:9]
	global_load_dwordx4 v[82:85], v1, s[8:9] offset:1024
	global_load_dwordx4 v[86:89], v1, s[8:9] offset:2048
	global_load_dwordx4 v[90:93], v1, s[8:9] offset:3072
	global_load_dwordx4 v[94:97], v1, s[18:19]
	s_add_u32 s8, s8, 0x8000
	s_addc_u32 s9, s9, 0
	s_add_u32 s18, s18, 0x2000
	s_addc_u32 s19, s19, 0
	s_add_u32 s14, s14, 0x8000
	s_addc_u32 s15, s15, 0
	s_andn2_b64 vcc, exec, s[34:35]
	s_cbranch_vccnz .Lp2b_pv_1
	global_load_dwordx4 v[170:173], v1, s[16:17]

; #define LAS __attribute__((address_space(3)))
; #define LDS_WAIT() asm volatile("s_waitcnt lgkmcnt(0)" ::: "memory")
; #define SCAN_LOADV(VSET, CH) do { const size_t c_ = (size_t)(CH); \
;             _Pragma("unroll") for (int s = 0; s < 4; ++s) kf[VSET][s] = *(const bf16x8*)(kp + c_ * 32768 + 1024 * s + voff); } while (0)
; #define SCAN_LOAD(SET, CH) do { const size_t c_ = (size_t)(CH); \
;             _Pragma("unroll") for (int nt = 0; nt < 2; ++nt) _Pragma("unroll") for (int s = 0; s < 2; ++s) qf[SET][nt][s] = *(const bf16x8*)(qp + c_ * 32768 + nt * 2048 + 1024 * s + voff); \
;             pf[SET] = *(const bf16x8*)(pp + c_ * 8192 + voff); } while (0)
; __device__ __forceinline__ void scan_phase(const bf16* q, const bf16* kdT, const bf16* vT, const bf16* Pp, bf16* o, LAS unsigned char* lds, int bid, int G, int wave, int lane, int tid) {
;     ...
;         SCAN_LOAD(0, 0); SCAN_LOAD(1, 1); SCAN_LOADV(0, 0);
;         vst = *(const bf16x8*)(vp + 1024 * (wave & 3) + voff);
;         if (wave < 4) { *(LAS bf16x8*)(lds + 65536 + wave * 1024 + voff) = vst; vst = *(const bf16x8*)(vp + (size_t)32768 + 1024 * wave + voff); }
;         LDS_WAIT(); __builtin_amdgcn_s_barrier(); asm volatile("" ::: "memory");
; #pragma unroll
;         for (int s = 0; s < 4; ++s) vf[s] = *(const LAS bf16x8*)(lds + 65536 + s * 1024 + voff);
;         for (int i = 0; i < 60; i += 6) { SCAN_STEP(0, 2, 0, 1, i); SCAN_STEP(1, 0, 1, 0, i + 1); SCAN_STEP(2, 1, 0, 1, i + 2); SCAN_STEP(0, 2, 1, 0, i + 3); SCAN_STEP(1, 0, 0, 1, i + 4); SCAN_STEP(2, 1, 1, 0, i + 5); }
;         SCAN_STEP(0, 2, 0, 1, 60); SCAN_STEP(1, 0, 1, 0, 61); SCAN_STEP(2, 1, 0, 1, 62); SCAN_STEP(0, 2, 1, 0, 63);
;     ...
;         __syncthreads();
.Lp2b_in_31:
	v_mfma_f32_32x32x16_bf16 v[2:17], v[134:137], v[150:153], v[2:17]
	v_mfma_f32_32x32x16_bf16 v[2:17], v[138:141], v[154:157], v[2:17]
	v_mfma_f32_32x32x16_bf16 v[2:17], v[142:145], v[158:161], v[2:17]
	v_mfma_f32_32x32x16_bf16 v[2:17], v[146:149], v[162:165], v[2:17]
	s_nop 7
	v_cvt_pk_bf16_f32 v18, v18, v19
	v_cvt_pk_bf16_f32 v19, v20, v21
	v_cvt_pk_bf16_f32 v20, v22, v23
	v_cvt_pk_bf16_f32 v21, v24, v25
	v_cvt_pk_bf16_f32 v22, v26, v27
	v_cvt_pk_bf16_f32 v23, v28, v29
	v_cvt_pk_bf16_f32 v24, v30, v31
	v_cvt_pk_bf16_f32 v25, v32, v33
	ds_write_b128 v192, v[18:21] offset:32768
	ds_write_b128 v192, v[22:25] offset:33792
	v_cvt_pk_bf16_f32 v34, v34, v35
	v_cvt_pk_bf16_f32 v35, v36, v37
	v_cvt_pk_bf16_f32 v36, v38, v39
	v_cvt_pk_bf16_f32 v37, v40, v41
	v_cvt_pk_bf16_f32 v38, v42, v43
	v_cvt_pk_bf16_f32 v39, v44, v45
	v_cvt_pk_bf16_f32 v40, v46, v47
	v_cvt_pk_bf16_f32 v41, v48, v49
	ds_write_b128 v192, v[34:37] offset:34816
	ds_write_b128 v192, v[38:41] offset:35840
	s_waitcnt lgkmcnt(0)
	s_barrier
	ds_read2st64_b64 v[18:21], v193 offset0:64 offset1:72
	ds_read2st64_b64 v[22:25], v193 offset0:80 offset1:88
	ds_read2st64_b64 v[26:29], v193 offset0:96 offset1:104
	ds_read2st64_b64 v[30:33], v193 offset0:112 offset1:120
	s_waitcnt lgkmcnt(3)
	v_lshlrev_b32_e32 v178, 16, v18
	v_and_b32_e32 v179, 0xffff0000, v18
	v_lshlrev_b32_e32 v180, 16, v19
	v_and_b32_e32 v181, 0xffff0000, v19
	v_add_f32_e32 v174, 0, v178
	v_add_f32_e32 v175, 0, v179
	v_add_f32_e32 v176, 0, v180
	v_add_f32_e32 v177, 0, v181
	v_lshlrev_b32_e32 v178, 16, v20
	v_and_b32_e32 v179, 0xffff0000, v20
	v_lshlrev_b32_e32 v180, 16, v21
	v_and_b32_e32 v181, 0xffff0000, v21
	v_add_f32_e32 v174, v174, v178
	v_add_f32_e32 v175, v175, v179
	v_add_f32_e32 v176, v176, v180
	v_add_f32_e32 v177, v177, v181
	s_waitcnt lgkmcnt(2)
	v_lshlrev_b32_e32 v178, 16, v22
	v_and_b32_e32 v179, 0xffff0000, v22
	v_lshlrev_b32_e32 v180, 16, v23
	v_and_b32_e32 v181, 0xffff0000, v23
	v_add_f32_e32 v174, v174, v178
	v_add_f32_e32 v175, v175, v179
	v_add_f32_e32 v176, v176, v180
	v_add_f32_e32 v177, v177, v181
	v_lshlrev_b32_e32 v178, 16, v24
	v_and_b32_e32 v179, 0xffff0000, v24
	v_lshlrev_b32_e32 v180, 16, v25
	v_and_b32_e32 v181, 0xffff0000, v25
	v_add_f32_e32 v174, v174, v178
	v_add_f32_e32 v175, v175, v179
	v_add_f32_e32 v176, v176, v180
	v_add_f32_e32 v177, v177, v181
	s_waitcnt lgkmcnt(1)
	v_lshlrev_b32_e32 v178, 16, v26
	v_and_b32_e32 v179, 0xffff0000, v26
	v_lshlrev_b32_e32 v180, 16, v27
	v_and_b32_e32 v181, 0xffff0000, v27
	v_add_f32_e32 v174, v174, v178
	v_add_f32_e32 v175, v175, v179
	v_add_f32_e32 v176, v176, v180
	v_add_f32_e32 v177, v177, v181
	v_lshlrev_b32_e32 v178, 16, v28
	v_and_b32_e32 v179, 0xffff0000, v28
	v_lshlrev_b32_e32 v180, 16, v29
	v_and_b32_e32 v181, 0xffff0000, v29
	v_add_f32_e32 v174, v174, v178
	v_add_f32_e32 v175, v175, v179
	v_add_f32_e32 v176, v176, v180
	v_add_f32_e32 v177, v177, v181
	s_waitcnt lgkmcnt(0)
	v_lshlrev_b32_e32 v178, 16, v30
	v_and_b32_e32 v179, 0xffff0000, v30
	v_lshlrev_b32_e32 v180, 16, v31
	v_and_b32_e32 v181, 0xffff0000, v31
	v_add_f32_e32 v174, v174, v178
	v_add_f32_e32 v175, v175, v179
	v_add_f32_e32 v176, v176, v180
	v_add_f32_e32 v177, v177, v181
	v_lshlrev_b32_e32 v178, 16, v32
	v_and_b32_e32 v179, 0xffff0000, v32
	v_lshlrev_b32_e32 v180, 16, v33
	v_and_b32_e32 v181, 0xffff0000, v33
	v_add_f32_e32 v174, v174, v178
	v_add_f32_e32 v175, v175, v179
	v_add_f32_e32 v176, v176, v180
	v_add_f32_e32 v177, v177, v181
	v_mul_f32_e32 v174, v186, v174
	v_mul_f32_e32 v175, v187, v175
	v_mul_f32_e32 v176, v188, v176
	v_mul_f32_e32 v177, v189, v177
	v_bfe_u32 v178, v174, 16, 1
	v_bfe_u32 v179, v175, 16, 1
	v_bfe_u32 v180, v176, 16, 1
	v_bfe_u32 v181, v177, 16, 1
	v_add3_u32 v174, v174, v178, s23
	v_add3_u32 v175, v175, v179, s23
	v_add3_u32 v176, v176, v180, s23
	v_add3_u32 v177, v177, v181, s23
	global_store_short_d16_hi v197, v174, s[20:21] offset:-4096
	global_store_short_d16_hi v197, v175, s[20:21]
	global_store_short_d16_hi v198, v176, s[20:21] offset:-4096
	global_store_short_d16_hi v198, v177, s[20:21]
	s_add_u32 s20, s20, 0x40000
	s_addc_u32 s21, s21, 0
	s_barrier
	s_branch .LBB0_718
; #define LAS __attribute__((address_space(3)))
; __device__ __forceinline__ float head_lg2(int h) { return log2f(1.0f - exp2f(-5.0f - (float)h)); }
; __device__ __forceinline__ void scan_phase(const bf16* q, const bf16* kdT, const bf16* vT, const bf16* Pp, bf16* o, LAS unsigned char* lds, int bid, int G, int wave, int lane, int tid) {
;     const int rnt = tid >> 8, rj = (tid >> 6) & 3, rhh = (tid >> 5) & 1, rv = tid & 31, rn0 = 32 * rnt + 8 * rj + 4 * rhh;
;     for (int unit = bid; unit < 256; unit += G) {
;         const int bh = (unit & 7) * 4 + (unit >> 6), vs = (unit >> 3) & 7, b = bh >> 3, h = bh & 7;
;         const float lg2 = head_lg2(h), cd = exp2f(64.0f * lg2);
;         float qd[4];
; #pragma unroll
;         for (int e = 0; e < 4; ++e) qd[e] = exp2f((float)(rn0 + e + 1) * lg2);
;         const char* kp = (const char*)kdT + ((size_t)bh * 64 * 16384 + wave * 2048) * 2;
;         const char* vp = (const char*)vT + ((size_t)bh * 64 * 16384 + vs * 2048) * 2;
;         const char* qp = (const char*)q + ((size_t)bh * 64 * 16384 + wave * 2048) * 2;
;         const char* pp = (const char*)Pp + ((size_t)bh * 64 * 4096 + wave * 512) * 2;
;         const unsigned voff = (unsigned)lane * 16u;
;         bf16* op = o + (size_t)(b * SEQ + rn0) * 2048 + h * 256 + 32 * vs + rv;
;         const int iks = wave & 3, int_ = wave >> 2;
;         const int rboff = ((rnt * 2 + (rj >> 1)) * 64 + rhh * 32 + rv) * 16 + (rj & 1) * 8;
.Lp2b_generic:
	s_add_u32 s57, s12, 0x5800000
	s_addc_u32 s58, s13, 0
	s_add_u32 s59, s12, 0x11800000
	s_addc_u32 s60, s13, 0
	s_add_u32 s61, s12, 0xd800000
	s_addc_u32 s62, s13, 0
	s_add_u32 s14, s12, 0x9800000
	s_addc_u32 s15, s13, 0
	s_ashr_i32 s1, s0, 6
	s_lshl_b32 s4, s1, 9
	s_lshl_b32 s16, s1, 11
	s_ashr_i32 s5, s4, 31
	s_ashr_i32 s17, s16, 31
	s_lshl_b64 s[4:5], s[4:5], 1
	s_add_u32 s6, s12, s4
	s_addc_u32 s7, s13, s5
	s_waitcnt vmcnt(28)
	v_ashrrev_i32_e32 v3, 8, v2
	s_waitcnt vmcnt(26)
	v_bfe_u32 v5, v2, 5, 1
	v_lshrrev_b32_e32 v6, 3, v2
	s_add_u32 s63, s6, 0x19800000
	v_lshlrev_b32_e32 v1, 5, v3
	v_and_b32_e32 v4, 24, v6
	s_waitcnt vmcnt(24)
	v_lshlrev_b32_e32 v7, 2, v5
	s_addc_u32 s64, s7, 0
	s_and_b32 s65, s1, 3
	v_or3_b32 v1, v4, v1, v7
	v_and_b32_e32 v4, 31, v2
	v_lshlrev_b32_e32 v8, 4, v2
	v_lshlrev_b32_e32 v3, 7, v3
	v_lshrrev_b32_e32 v2, 1, v2
	s_lshl_b32 s66, s65, 10
	v_and_or_b32 v2, v2, 64, v3
	v_lshlrev_b32_e32 v3, 5, v5
	s_cmp_lt_i32 s1, 4
	v_and_b32_e32 v166, 0x3f0, v8
	v_or3_b32 v2, v2, v3, v4
	v_and_b32_e32 v3, 8, v6
	s_cselect_b64 s[22:23], -1, 0
	s_lshl_b32 s67, s1, 10
	s_add_i32 s6, 0, 0x10000
	v_lshl_or_b32 v2, v2, 4, v3
	s_add_i32 s70, s6, s67
	v_add_u32_e32 v177, s6, v166
	s_add_i32 s71, 0, 0x11000
	s_lshl_b32 s6, s1, 12
	v_or_b32_e32 v3, 2, v1
	s_load_dword s56, s[84:85], 0x0
	s_ashr_i32 s69, s67, 31
	v_add_u32_e32 v204, s71, v166
	s_add_i32 s6, s6, 0
	s_add_i32 s71, s71, s67
	v_cvt_f32_i32_e32 v207, v3
	v_or_b32_e32 v3, 3, v1
	v_or_b32_e32 v7, 1, v1
	v_cvt_f32_i32_e32 v208, v3
	v_add_u32_e32 v3, 4, v1
	s_cmp_lt_u32 s1, 4
	v_cvt_f32_i32_e32 v206, v7
	v_cvt_f32_i32_e32 v209, v3
	s_cselect_b64 s[38:39], -1, 0
	s_and_b32 s0, s0, 0xffffff00
	s_cmpk_eq_i32 s0, 0x100
	v_mov_b32_e32 v169, 0
	s_cselect_b64 s[40:41], -1, 0
	s_lshl_b64 s[0:1], s[16:17], 1
	s_mov_b32 s21, 0
	v_mov_b32_e32 v167, v169
	v_add_u32_e32 v205, s6, v166
	v_or_b32_e32 v170, s67, v166
	v_mov_b32_e32 v171, s69
	s_lshl_b32 s72, s2, 2
	s_waitcnt lgkmcnt(0)
	s_lshl_b32 s73, s56, 2
	v_or_b32_e32 v172, s4, v166
	v_mov_b32_e32 v173, s5
	v_or_b32_e32 v174, s0, v166
	v_mov_b32_e32 v175, s1
	v_lshlrev_b32_e32 v176, 1, v4
	v_cndmask_b32_e64 v210, 0, 1, s[22:23]
	s_mov_b32 s74, 0xc2fc0000
	s_movk_i32 s75, 0x7fff
	s_mov_b32 s76, 0x9841000
	s_mov_b32 s77, 0x9842000
	s_mov_b32 s78, 0x9881000
	s_mov_b32 s79, 0x9882000
	s_mov_b32 s80, 0x98c1000
	s_mov_b32 s81, 0x98c2000
	s_mov_b32 s82, 0x9901000
	s_mov_b32 s83, 0x9902000
	s_mov_b32 s84, 0x9941000
	s_mov_b32 s85, 0x9943000
	s_mov_b64 s[42:43], 0x30000
	s_mov_b64 s[44:45], 0xc000
	s_mov_b64 s[46:47], 0x180000
	s_mov_b32 s86, 0x1f0000
	s_mov_b64 s[48:49], 0x1f0000
	s_mov_b64 s[50:51], 0x1e8000
	v_lshlrev_b32_e32 v168, 1, v4
	s_mov_b32 s87, 0xf01000
	s_mov_b32 s88, 0xf02000
	s_mov_b64 s[52:53], 0x1f8000
	s_mov_b32 s89, 0xf41000
	s_mov_b32 s90, 0xf42000
	s_mov_b32 s91, 0xf81000
	s_mov_b32 s92, 0xf82000
	s_mov_b32 s93, 0xfc1000
	s_mov_b32 s94, 0xfc2000
	v_mov_b32_e32 v211, 0x42800000
	v_mov_b32_e32 v212, 0x42000000
	v_not_b32_e32 v213, 63
	v_add_u32_e32 v214, 0, v2
	s_mov_b32 s95, s2
	s_branch .LBB0_435

; template <class Epi, class Sched, bool ALIGN_EPI = false, bool SP2 = false>
; __device__ __forceinline__ void gemm_phase(PG8_LAS unsigned char* lds, const Gemm g, const Sched& S, const Epi& E) {
;     ...
;         const bool has_next = S.next(ui + 1, nxt);
;         const char* nA = has_next ? (const char*)g.A + (size_t)nxt.pm * tA + (size_t)nxt.pn * pnA : cA; const char* nB = has_next ? (const char*)g.Bt + (size_t)nxt.pn * tB : cB;
;     ...
;         for (int a = 0; a < 2; ++a)
; #pragma unroll
;             for (int b = 0; b < 2; ++b)
; #pragma unroll
;                 for (int m = 0; m < 4; ++m)
; #pragma unroll
;                     for (int n = 0; n < 2; ++n) acc[a][b][m][n] = (f32x4){0.f, 0.f, 0.f, 0.f};
;         cur = nxt; cA = nA; cB = nB; ++ui;
.LBB0_784:
	s_ashr_i32 s45, s44, 31
	s_lshl_b64 s[48:49], s[44:45], 19
	s_add_u32 s18, s67, s48
	s_addc_u32 s19, s69, s49
	s_ashr_i32 s41, s40, 31
	s_lshl_b64 s[48:49], s[40:41], 9
	s_add_u32 s48, s18, s48
	s_addc_u32 s49, s19, s49
	s_and_b64 s[50:51], s[4:5], exec
	s_cselect_b32 s45, s49, s47
	s_cselect_b32 s87, s48, s46
	s_lshl_b64 s[50:51], s[40:41], 17
	s_add_u32 s50, s70, s50
	s_addc_u32 s51, s71, s51
	s_and_b64 s[52:53], s[4:5], exec
	v_mov_b32_e32 v2, 0
	s_cselect_b32 s41, s51, s43
	s_cselect_b32 s88, s50, s42
	s_mov_b64 s[56:57], 0
	s_mov_b64 s[52:53], -1
	s_mov_b64 s[54:55], 0
	v_mov_b32_e32 v3, v2
	v_mov_b64_e32 v[4:5], 0
	v_mov_b64_e32 v[6:7], 0
	v_mov_b64_e32 v[8:9], 0
	v_mov_b64_e32 v[10:11], 0
	v_mov_b64_e32 v[12:13], 0
	v_mov_b64_e32 v[14:15], 0
	v_mov_b64_e32 v[16:17], 0
	v_mov_b64_e32 v[18:19], 0
	v_mov_b64_e32 v[20:21], 0
	v_mov_b64_e32 v[22:23], 0
	v_mov_b64_e32 v[24:25], 0
	v_mov_b64_e32 v[26:27], 0
	v_mov_b64_e32 v[28:29], 0
	v_mov_b64_e32 v[30:31], 0
	v_mov_b64_e32 v[32:33], 0
	v_mov_b64_e32 v[34:35], 0
	v_mov_b64_e32 v[36:37], 0
	v_mov_b64_e32 v[38:39], 0
	v_mov_b64_e32 v[40:41], 0
	v_mov_b64_e32 v[42:43], 0
	v_mov_b64_e32 v[44:45], 0
	v_mov_b64_e32 v[46:47], 0
	v_mov_b64_e32 v[48:49], 0
	v_mov_b64_e32 v[50:51], 0
	v_mov_b64_e32 v[52:53], 0
	v_mov_b64_e32 v[54:55], 0
	v_mov_b64_e32 v[56:57], 0
	v_mov_b64_e32 v[58:59], 0
	v_mov_b64_e32 v[60:61], 0
	v_mov_b64_e32 v[62:63], 0
	v_mov_b64_e32 v[64:65], 0
	v_mov_b64_e32 v[66:67], 0
	v_mov_b64_e32 v[68:69], 0
	v_mov_b64_e32 v[70:71], 0
	v_mov_b64_e32 v[72:73], 0
	v_mov_b64_e32 v[74:75], 0
	v_mov_b64_e32 v[76:77], 0
	v_mov_b64_e32 v[78:79], 0
	v_mov_b64_e32 v[80:81], 0
	v_mov_b64_e32 v[82:83], 0
	v_mov_b64_e32 v[84:85], 0
	v_mov_b64_e32 v[86:87], 0
	v_mov_b64_e32 v[88:89], 0
	v_mov_b64_e32 v[90:91], 0
	v_mov_b64_e32 v[92:93], 0
	v_mov_b64_e32 v[94:95], 0
	v_mov_b64_e32 v[96:97], 0
	v_mov_b64_e32 v[98:99], 0
	v_mov_b64_e32 v[100:101], 0
	v_mov_b64_e32 v[102:103], 0
	v_mov_b64_e32 v[104:105], 0
	v_mov_b64_e32 v[106:107], 0
	v_mov_b64_e32 v[108:109], 0
	v_mov_b64_e32 v[110:111], 0
	v_mov_b64_e32 v[112:113], 0
	v_mov_b64_e32 v[114:115], 0
	v_mov_b64_e32 v[116:117], 0
	v_mov_b64_e32 v[118:119], 0
	v_mov_b64_e32 v[120:121], 0
	v_mov_b64_e32 v[122:123], 0
	v_mov_b64_e32 v[124:125], 0
	v_mov_b64_e32 v[126:127], 0
	v_mov_b64_e32 v[128:129], 0

; template <class Epi, class Sched, bool ALIGN_EPI = false, bool SP2 = false>
; __device__ __forceinline__ void gemm_phase(PG8_LAS unsigned char* lds, const Gemm g, const Sched& S, const Epi& E) {
;     ...
;         const bool has_next = S.next(ui + 1, nxt);
;         const char* nA = has_next ? (const char*)g.A + (size_t)nxt.pm * tA + (size_t)nxt.pn * pnA : cA; const char* nB = has_next ? (const char*)g.Bt + (size_t)nxt.pn * tB : cB;
;     ...
;         for (int a = 0; a < 2; ++a)
; #pragma unroll
;             for (int b = 0; b < 2; ++b)
; #pragma unroll
;                 for (int m = 0; m < 4; ++m)
; #pragma unroll
;                     for (int n = 0; n < 2; ++n) acc[a][b][m][n] = (f32x4){0.f, 0.f, 0.f, 0.f};
;         cur = nxt; cA = nA; cB = nB; ++ui;
.LBB0_867:
	s_ashr_i32 s23, s22, 31
	s_lshl_b64 s[24:25], s[22:23], 19
	s_add_u32 s24, s33, s24
	s_addc_u32 s25, s48, s25
	s_and_b64 s[38:39], s[4:5], exec
	s_cselect_b32 s23, s25, s43
	s_cselect_b32 s67, s24, s42
	s_ashr_i32 s21, s20, 31
	s_lshl_b64 s[38:39], s[20:21], 19
	s_add_u32 s38, s49, s38
	s_addc_u32 s39, s51, s39
	s_and_b64 s[46:47], s[4:5], exec
	s_cselect_b32 s21, s39, s45
	s_cselect_b32 s69, s38, s44
	s_add_u32 s42, s42, 0x40080
	s_addc_u32 s43, s43, 0
	s_add_u32 s70, s44, 0x100
	v_mov_b32_e32 v2, 0
	s_addc_u32 s71, s45, 0
	s_mov_b32 s72, -2
	v_mov_b32_e32 v3, v2
	v_mov_b64_e32 v[4:5], 0
	v_mov_b64_e32 v[6:7], 0
	v_mov_b64_e32 v[8:9], 0
	v_mov_b64_e32 v[10:11], 0
	v_mov_b64_e32 v[12:13], 0
	v_mov_b64_e32 v[14:15], 0
	v_mov_b64_e32 v[16:17], 0
	v_mov_b64_e32 v[18:19], 0
	v_mov_b64_e32 v[20:21], 0
	v_mov_b64_e32 v[22:23], 0
	v_mov_b64_e32 v[24:25], 0
	v_mov_b64_e32 v[26:27], 0
	v_mov_b64_e32 v[28:29], 0
	v_mov_b64_e32 v[30:31], 0
	v_mov_b64_e32 v[32:33], 0
	v_mov_b64_e32 v[34:35], 0
	v_mov_b64_e32 v[36:37], 0
	v_mov_b64_e32 v[38:39], 0
	v_mov_b64_e32 v[40:41], 0
	v_mov_b64_e32 v[42:43], 0
	v_mov_b64_e32 v[44:45], 0
	v_mov_b64_e32 v[46:47], 0
	v_mov_b64_e32 v[48:49], 0
	v_mov_b64_e32 v[50:51], 0
	v_mov_b64_e32 v[52:53], 0
	v_mov_b64_e32 v[54:55], 0
	v_mov_b64_e32 v[56:57], 0
	v_mov_b64_e32 v[58:59], 0
	v_mov_b64_e32 v[60:61], 0
	v_mov_b64_e32 v[62:63], 0
	v_mov_b64_e32 v[64:65], 0
	v_mov_b64_e32 v[66:67], 0
	v_mov_b64_e32 v[68:69], 0
	v_mov_b64_e32 v[70:71], 0
	v_mov_b64_e32 v[72:73], 0
	v_mov_b64_e32 v[74:75], 0
	v_mov_b64_e32 v[76:77], 0
	v_mov_b64_e32 v[78:79], 0
	v_mov_b64_e32 v[80:81], 0
	v_mov_b64_e32 v[82:83], 0
	v_mov_b64_e32 v[84:85], 0
	v_mov_b64_e32 v[86:87], 0
	v_mov_b64_e32 v[88:89], 0
	v_mov_b64_e32 v[90:91], 0
	v_mov_b64_e32 v[92:93], 0
	v_mov_b64_e32 v[94:95], 0
	v_mov_b64_e32 v[96:97], 0
	v_mov_b64_e32 v[98:99], 0
	v_mov_b64_e32 v[100:101], 0
	v_mov_b64_e32 v[102:103], 0
	v_mov_b64_e32 v[104:105], 0
	v_mov_b64_e32 v[106:107], 0
	v_mov_b64_e32 v[108:109], 0
	v_mov_b64_e32 v[110:111], 0
	v_mov_b64_e32 v[112:113], 0
	v_mov_b64_e32 v[114:115], 0
	v_mov_b64_e32 v[116:117], 0
	v_mov_b64_e32 v[118:119], 0
	v_mov_b64_e32 v[120:121], 0
	v_mov_b64_e32 v[122:123], 0
	v_mov_b64_e32 v[124:125], 0
	v_mov_b64_e32 v[126:127], 0
	v_mov_b64_e32 v[128:129], 0

; template <class Epi, class Sched, bool ALIGN_EPI = false, bool SP2 = false>
; __device__ __forceinline__ void gemm_phase(PG8_LAS unsigned char* lds, const Gemm g, const Sched& S, const Epi& E) {
;     ...
;         const bool has_next = S.next(ui + 1, nxt);
;         const char* nA = has_next ? (const char*)g.A + (size_t)nxt.pm * tA + (size_t)nxt.pn * pnA : cA; const char* nB = has_next ? (const char*)g.Bt + (size_t)nxt.pn * tB : cB;
;     ...
;         for (int a = 0; a < 2; ++a)
; #pragma unroll
;             for (int b = 0; b < 2; ++b)
; #pragma unroll
;                 for (int m = 0; m < 4; ++m)
; #pragma unroll
;                     for (int n = 0; n < 2; ++n) acc[a][b][m][n] = (f32x4){0.f, 0.f, 0.f, 0.f};
;         cur = nxt; cA = nA; cB = nB; ++ui;
.LBB0_887:
	s_ashr_i32 s25, s24, 31
	s_lshl_b64 s[38:39], s[24:25], 20
	s_add_u32 s38, s33, s38
	s_addc_u32 s39, s51, s39
	s_and_b64 s[40:41], s[6:7], exec
	s_cselect_b32 s25, s39, s45
	s_cselect_b32 s70, s38, s44
	s_ashr_i32 s23, s22, 31
	s_lshl_b64 s[40:41], s[22:23], 20
	s_add_u32 s40, s52, s40
	s_addc_u32 s41, s53, s41
	s_and_b64 s[48:49], s[6:7], exec
	s_cselect_b32 s23, s41, s47
	s_cselect_b32 s71, s40, s46
	s_add_u32 s44, s44, 0x80080
	s_addc_u32 s45, s45, 0
	s_add_u32 s72, s46, 0x100
	v_mov_b32_e32 v2, 0
	s_addc_u32 s73, s47, 0
	s_mov_b32 s74, -2
	v_mov_b32_e32 v3, v2
	v_mov_b64_e32 v[4:5], 0
	v_mov_b64_e32 v[6:7], 0
	v_mov_b64_e32 v[8:9], 0
	v_mov_b64_e32 v[10:11], 0
	v_mov_b64_e32 v[12:13], 0
	v_mov_b64_e32 v[14:15], 0
	v_mov_b64_e32 v[16:17], 0
	v_mov_b64_e32 v[18:19], 0
	v_mov_b64_e32 v[20:21], 0
	v_mov_b64_e32 v[22:23], 0
	v_mov_b64_e32 v[24:25], 0
	v_mov_b64_e32 v[26:27], 0
	v_mov_b64_e32 v[28:29], 0
	v_mov_b64_e32 v[30:31], 0
	v_mov_b64_e32 v[32:33], 0
	v_mov_b64_e32 v[34:35], 0
	v_mov_b64_e32 v[36:37], 0
	v_mov_b64_e32 v[38:39], 0
	v_mov_b64_e32 v[40:41], 0
	v_mov_b64_e32 v[42:43], 0
	v_mov_b64_e32 v[44:45], 0
	v_mov_b64_e32 v[46:47], 0
	v_mov_b64_e32 v[48:49], 0
	v_mov_b64_e32 v[50:51], 0
	v_mov_b64_e32 v[52:53], 0
	v_mov_b64_e32 v[54:55], 0
	v_mov_b64_e32 v[56:57], 0
	v_mov_b64_e32 v[58:59], 0
	v_mov_b64_e32 v[60:61], 0
	v_mov_b64_e32 v[62:63], 0
	v_mov_b64_e32 v[64:65], 0
	v_mov_b64_e32 v[66:67], 0
	v_mov_b64_e32 v[68:69], 0
	v_mov_b64_e32 v[70:71], 0
	v_mov_b64_e32 v[72:73], 0
	v_mov_b64_e32 v[74:75], 0
	v_mov_b64_e32 v[76:77], 0
	v_mov_b64_e32 v[78:79], 0
	v_mov_b64_e32 v[80:81], 0
	v_mov_b64_e32 v[82:83], 0
	v_mov_b64_e32 v[84:85], 0
	v_mov_b64_e32 v[86:87], 0
	v_mov_b64_e32 v[88:89], 0
	v_mov_b64_e32 v[90:91], 0
	v_mov_b64_e32 v[92:93], 0
	v_mov_b64_e32 v[94:95], 0
	v_mov_b64_e32 v[96:97], 0
	v_mov_b64_e32 v[98:99], 0
	v_mov_b64_e32 v[100:101], 0
	v_mov_b64_e32 v[102:103], 0
	v_mov_b64_e32 v[104:105], 0
	v_mov_b64_e32 v[106:107], 0
	v_mov_b64_e32 v[108:109], 0
	v_mov_b64_e32 v[110:111], 0
	v_mov_b64_e32 v[112:113], 0
	v_mov_b64_e32 v[114:115], 0
	v_mov_b64_e32 v[116:117], 0
	v_mov_b64_e32 v[118:119], 0
	v_mov_b64_e32 v[120:121], 0
	v_mov_b64_e32 v[122:123], 0
	v_mov_b64_e32 v[124:125], 0
	v_mov_b64_e32 v[126:127], 0
	v_mov_b64_e32 v[128:129], 0

; template <class Epi, class Sched, bool ALIGN_EPI = false, bool SP2 = false>
; __device__ __forceinline__ void gemm_phase(PG8_LAS unsigned char* lds, const Gemm g, const Sched& S, const Epi& E) {
;     ...
;         const bool has_next = S.next(ui + 1, nxt);
;         const char* nA = has_next ? (const char*)g.A + (size_t)nxt.pm * tA + (size_t)nxt.pn * pnA : cA; const char* nB = has_next ? (const char*)g.Bt + (size_t)nxt.pn * tB : cB;
;     ...
;         for (int a = 0; a < 2; ++a)
; #pragma unroll
;             for (int b = 0; b < 2; ++b)
; #pragma unroll
;                 for (int m = 0; m < 4; ++m)
; #pragma unroll
;                     for (int n = 0; n < 2; ++n) acc[a][b][m][n] = (f32x4){0.f, 0.f, 0.f, 0.f};
;         cur = nxt; cA = nA; cB = nB; ++ui;
.LBB0_962:
	s_ashr_i32 s41, s40, 31
	s_lshl_b64 s[42:43], s[40:41], 20
	s_add_u32 s42, s33, s42
	s_addc_u32 s43, s58, s43
	s_and_b64 s[44:45], s[8:9], exec
	s_cselect_b32 s41, s43, s49
	s_cselect_b32 s47, s42, s48
	s_ashr_i32 s39, s38, 31
	s_lshl_b64 s[44:45], s[38:39], 20
	s_add_u32 s44, s59, s44
	s_addc_u32 s45, s60, s45
	s_and_b64 s[52:53], s[8:9], exec
	s_cselect_b32 s39, s45, s51
	s_cselect_b32 s75, s44, s50
	s_add_u32 s48, s48, 0x80080
	s_addc_u32 s49, s49, 0
	s_add_u32 s76, s50, 0x100
	v_mov_b32_e32 v2, 0
	s_addc_u32 s77, s51, 0
	s_mov_b32 s78, -2
	s_waitcnt lgkmcnt(0)
	v_mov_b32_e32 v3, v2
	v_mov_b64_e32 v[4:5], 0
	v_mov_b64_e32 v[6:7], 0
	v_mov_b64_e32 v[8:9], 0
	v_mov_b64_e32 v[10:11], 0
	v_mov_b64_e32 v[12:13], 0
	v_mov_b64_e32 v[14:15], 0
	v_mov_b64_e32 v[16:17], 0
	v_mov_b64_e32 v[18:19], 0
	v_mov_b64_e32 v[20:21], 0
	v_mov_b64_e32 v[22:23], 0
	v_mov_b64_e32 v[24:25], 0
	v_mov_b64_e32 v[26:27], 0
	v_mov_b64_e32 v[28:29], 0
	v_mov_b64_e32 v[30:31], 0
	v_mov_b64_e32 v[32:33], 0
	v_mov_b64_e32 v[34:35], 0
	v_mov_b64_e32 v[36:37], 0
	v_mov_b64_e32 v[38:39], 0
	v_mov_b64_e32 v[40:41], 0
	v_mov_b64_e32 v[42:43], 0
	v_mov_b64_e32 v[44:45], 0
	v_mov_b64_e32 v[46:47], 0
	v_mov_b64_e32 v[48:49], 0
	v_mov_b64_e32 v[50:51], 0
	v_mov_b64_e32 v[52:53], 0
	v_mov_b64_e32 v[54:55], 0
	v_mov_b64_e32 v[56:57], 0
	v_mov_b64_e32 v[58:59], 0
	v_mov_b64_e32 v[60:61], 0
	v_mov_b64_e32 v[62:63], 0
	v_mov_b64_e32 v[64:65], 0
	v_mov_b64_e32 v[66:67], 0
	v_mov_b64_e32 v[68:69], 0
	v_mov_b64_e32 v[70:71], 0
	v_mov_b64_e32 v[72:73], 0
	v_mov_b64_e32 v[74:75], 0
	v_mov_b64_e32 v[76:77], 0
	v_mov_b64_e32 v[78:79], 0
	v_mov_b64_e32 v[80:81], 0
	v_mov_b64_e32 v[82:83], 0
	v_mov_b64_e32 v[84:85], 0
	v_mov_b64_e32 v[86:87], 0
	v_mov_b64_e32 v[88:89], 0
	v_mov_b64_e32 v[90:91], 0
	v_mov_b64_e32 v[92:93], 0
	v_mov_b64_e32 v[94:95], 0
	v_mov_b64_e32 v[96:97], 0
	v_mov_b64_e32 v[98:99], 0
	v_mov_b64_e32 v[100:101], 0
	v_mov_b64_e32 v[102:103], 0
	v_mov_b64_e32 v[104:105], 0
	v_mov_b64_e32 v[106:107], 0
	v_mov_b64_e32 v[108:109], 0
	v_mov_b64_e32 v[110:111], 0
	v_mov_b64_e32 v[112:113], 0
	v_mov_b64_e32 v[114:115], 0
	v_mov_b64_e32 v[116:117], 0
	v_mov_b64_e32 v[118:119], 0
	v_mov_b64_e32 v[120:121], 0
	v_mov_b64_e32 v[122:123], 0
	v_mov_b64_e32 v[124:125], 0
	v_mov_b64_e32 v[126:127], 0
	v_mov_b64_e32 v[128:129], 0

; template <class Epi, class Sched, bool ALIGN_EPI = false, bool SP2 = false>
; __device__ __forceinline__ void gemm_phase(PG8_LAS unsigned char* lds, const Gemm g, const Sched& S, const Epi& E) {
;     ...
;         const bool has_next = S.next(ui + 1, nxt);
;         const char* nA = has_next ? (const char*)g.A + (size_t)nxt.pm * tA + (size_t)nxt.pn * pnA : cA; const char* nB = has_next ? (const char*)g.Bt + (size_t)nxt.pn * tB : cB;
;     ...
;         for (int a = 0; a < 2; ++a)
; #pragma unroll
;             for (int b = 0; b < 2; ++b)
; #pragma unroll
;                 for (int m = 0; m < 4; ++m)
; #pragma unroll
;                     for (int n = 0; n < 2; ++n) acc[a][b][m][n] = (f32x4){0.f, 0.f, 0.f, 0.f};
;         cur = nxt; cA = nA; cB = nB; ++ui;
.LBB0_1047:
	s_ashr_i32 s37, s36, 31
	s_lshl_b64 s[38:39], s[36:37], 20
	s_add_u32 s38, s33, s38
	s_addc_u32 s39, s46, s39
	s_and_b64 s[40:41], s[6:7], exec
	s_cselect_b32 s1, s39, s9
	s_cselect_b32 s37, s38, s8
	s_ashr_i32 s25, s24, 31
	s_lshl_b64 s[40:41], s[24:25], 20
	s_add_u32 s40, s47, s40
	s_addc_u32 s41, s48, s41
	s_and_b64 s[44:45], s[6:7], exec
	s_cselect_b32 s25, s41, s43
	s_cselect_b32 s69, s40, s42
	s_add_u32 s8, s8, 0x80080
	s_addc_u32 s9, s9, 0
	s_add_u32 s70, s42, 0x100
	v_mov_b32_e32 v2, 0
	s_addc_u32 s71, s43, 0
	s_mov_b32 s72, -2
	v_mov_b32_e32 v3, v2
	v_mov_b64_e32 v[4:5], 0
	v_mov_b64_e32 v[6:7], 0
	v_mov_b64_e32 v[8:9], 0
	v_mov_b64_e32 v[10:11], 0
	v_mov_b64_e32 v[12:13], 0
	v_mov_b64_e32 v[14:15], 0
	v_mov_b64_e32 v[16:17], 0
	v_mov_b64_e32 v[18:19], 0
	v_mov_b64_e32 v[20:21], 0
	v_mov_b64_e32 v[22:23], 0
	v_mov_b64_e32 v[24:25], 0
	v_mov_b64_e32 v[26:27], 0
	v_mov_b64_e32 v[28:29], 0
	v_mov_b64_e32 v[30:31], 0
	v_mov_b64_e32 v[32:33], 0
	v_mov_b64_e32 v[34:35], 0
	v_mov_b64_e32 v[36:37], 0
	v_mov_b64_e32 v[38:39], 0
	v_mov_b64_e32 v[40:41], 0
	v_mov_b64_e32 v[42:43], 0
	v_mov_b64_e32 v[44:45], 0
	v_mov_b64_e32 v[46:47], 0
	v_mov_b64_e32 v[48:49], 0
	v_mov_b64_e32 v[50:51], 0
	v_mov_b64_e32 v[52:53], 0
	v_mov_b64_e32 v[54:55], 0
	v_mov_b64_e32 v[56:57], 0
	v_mov_b64_e32 v[58:59], 0
	v_mov_b64_e32 v[60:61], 0
	v_mov_b64_e32 v[62:63], 0
	v_mov_b64_e32 v[64:65], 0
	v_mov_b64_e32 v[66:67], 0
	v_mov_b64_e32 v[68:69], 0
	v_mov_b64_e32 v[70:71], 0
	v_mov_b64_e32 v[72:73], 0
	v_mov_b64_e32 v[74:75], 0
	v_mov_b64_e32 v[76:77], 0
	v_mov_b64_e32 v[78:79], 0
	v_mov_b64_e32 v[80:81], 0
	v_mov_b64_e32 v[82:83], 0
	v_mov_b64_e32 v[84:85], 0
	v_mov_b64_e32 v[86:87], 0
	v_mov_b64_e32 v[88:89], 0
	v_mov_b64_e32 v[90:91], 0
	v_mov_b64_e32 v[92:93], 0
	v_mov_b64_e32 v[94:95], 0
	v_mov_b64_e32 v[96:97], 0
	v_mov_b64_e32 v[98:99], 0
	v_mov_b64_e32 v[100:101], 0
	v_mov_b64_e32 v[102:103], 0
	v_mov_b64_e32 v[104:105], 0
	v_mov_b64_e32 v[106:107], 0
	v_mov_b64_e32 v[108:109], 0
	v_mov_b64_e32 v[110:111], 0
	v_mov_b64_e32 v[112:113], 0
	v_mov_b64_e32 v[114:115], 0
	v_mov_b64_e32 v[116:117], 0
	v_mov_b64_e32 v[118:119], 0
	v_mov_b64_e32 v[120:121], 0
	v_mov_b64_e32 v[122:123], 0
	v_mov_b64_e32 v[124:125], 0
	v_mov_b64_e32 v[126:127], 0
	v_mov_b64_e32 v[128:129], 0

; template <class Epi, class Sched, bool ALIGN_EPI = false, bool SP2 = false>
; __device__ __forceinline__ void gemm_phase(PG8_LAS unsigned char* lds, const Gemm g, const Sched& S, const Epi& E) {
;     ...
;         for (int a = 0; a < 2; ++a)
; #pragma unroll
;             for (int b = 0; b < 2; ++b)
; #pragma unroll
;                 for (int m = 0; m < 4; ++m)
; #pragma unroll
;                     for (int n = 0; n < 2; ++n) acc[a][b][m][n] = (f32x4){0.f, 0.f, 0.f, 0.f};
;         cur = nxt; cA = nA; cB = nB; ++ui;
.LBB0_1126:
	s_add_u32 s61, s36, 0x100
	v_mov_b32_e32 v2, 0
	s_addc_u32 s62, s37, 0
	s_mov_b32 s63, -2
	s_waitcnt lgkmcnt(0)
	v_mov_b32_e32 v3, v2
	v_mov_b64_e32 v[4:5], 0
	v_mov_b64_e32 v[6:7], 0
	v_mov_b64_e32 v[8:9], 0
	v_mov_b64_e32 v[10:11], 0
	v_mov_b64_e32 v[12:13], 0
	v_mov_b64_e32 v[14:15], 0
	v_mov_b64_e32 v[16:17], 0
	v_mov_b64_e32 v[18:19], 0
	v_mov_b64_e32 v[20:21], 0
	v_mov_b64_e32 v[22:23], 0
	v_mov_b64_e32 v[24:25], 0
	v_mov_b64_e32 v[26:27], 0
	v_mov_b64_e32 v[28:29], 0
	v_mov_b64_e32 v[30:31], 0
	v_mov_b64_e32 v[32:33], 0
	v_mov_b64_e32 v[34:35], 0
	v_mov_b64_e32 v[36:37], 0
	v_mov_b64_e32 v[38:39], 0
	v_mov_b64_e32 v[40:41], 0
	v_mov_b64_e32 v[42:43], 0
	v_mov_b64_e32 v[44:45], 0
	v_mov_b64_e32 v[46:47], 0
	v_mov_b64_e32 v[48:49], 0
	v_mov_b64_e32 v[50:51], 0
	v_mov_b64_e32 v[52:53], 0
	v_mov_b64_e32 v[54:55], 0
	v_mov_b64_e32 v[56:57], 0
	v_mov_b64_e32 v[58:59], 0
	v_mov_b64_e32 v[60:61], 0
	v_mov_b64_e32 v[62:63], 0
	v_mov_b64_e32 v[64:65], 0
	v_mov_b64_e32 v[66:67], 0
	v_mov_b64_e32 v[68:69], 0
	v_mov_b64_e32 v[70:71], 0
	v_mov_b64_e32 v[72:73], 0
	v_mov_b64_e32 v[74:75], 0
	v_mov_b64_e32 v[76:77], 0
	v_mov_b64_e32 v[78:79], 0
	v_mov_b64_e32 v[80:81], 0
	v_mov_b64_e32 v[82:83], 0
	v_mov_b64_e32 v[84:85], 0
	v_mov_b64_e32 v[86:87], 0
	v_mov_b64_e32 v[88:89], 0
	v_mov_b64_e32 v[90:91], 0
	v_mov_b64_e32 v[92:93], 0
	v_mov_b64_e32 v[94:95], 0
	v_mov_b64_e32 v[96:97], 0
	v_mov_b64_e32 v[98:99], 0
	v_mov_b64_e32 v[100:101], 0
	v_mov_b64_e32 v[102:103], 0
	v_mov_b64_e32 v[104:105], 0
	v_mov_b64_e32 v[106:107], 0
	v_mov_b64_e32 v[108:109], 0
	v_mov_b64_e32 v[110:111], 0
	v_mov_b64_e32 v[112:113], 0
	v_mov_b64_e32 v[114:115], 0
	v_mov_b64_e32 v[116:117], 0
	v_mov_b64_e32 v[118:119], 0
	v_mov_b64_e32 v[120:121], 0
	v_mov_b64_e32 v[122:123], 0
	v_mov_b64_e32 v[124:125], 0
	v_mov_b64_e32 v[126:127], 0
	v_mov_b64_e32 v[128:129], 0
